# tile-order index math: L%8 and L/8 by and/shift with constant multiplier (L is non-negative) in 3 RSTD fill loops and 3 tile loops; RSTD loop exit test on the scalar unit instead of a 64-bit VALU comp
# speedup vs baseline: 1.0023x; 1.0023x over previous
;     __device__ __forceinline__ float rstd_global(int row) const { return row_rstd(ssq, row); }
;     __device__ __forceinline__ float rstd_global(int row) const { return row_rstd(ssq, row); }
;     __device__ __forceinline__ float rstd_global(int row) const { return row_rstd(ssq, row); }
;     __host__ __device__ bool next(int i, Unit& u) const {
;         const long L = (long)i * G + c; if (L >= nwg) return false;
;         int wgid = (int)L; { const int q = nwg / NXCD, r = nwg % NXCD, xcd = wgid % NXCD, off = wgid / NXCD; wgid = (xcd < r ? xcd * (q + 1) : r * (q + 1) + (xcd - r) * q) + off; }
;         const int nig = WGM * nN, gid = wgid / nig, fm = gid * WGM, gsz = (nM - fm) < WGM ? (nM - fm) : WGM;
;         u.pm = fm + ((wgid % nig) % gsz); u.pn = (wgid % nig) / gsz; return true;
; template <class Epi, class Sched, bool ALIGN_EPI = false, bool SP2 = false>
; __device__ __forceinline__ void gemm_phase(PG8_LAS unsigned char* lds, const Gemm g, const Sched& S, const Epi& E) {
;     ...
;         for (int i = 0; S.next(i, tu); ++i) {
;             const int p = tu.pm;
;             if (p != pmc0 && p != pmc1 && p != pmc2 && p != pmc3) {
;                 int slot = -1;
;                 if (pmc0 < 0) { pmc0 = p; slot = 0; } else if (pmc1 < 0) { pmc1 = p; slot = 1; } else if (pmc2 < 0) { pmc2 = p; slot = 2; } else if (pmc3 < 0) { pmc3 = p; slot = 3; }
;                 if (slot >= 0 && tid < 256) rt[slot * 256 + tid] = E.rstd_global(p * 256 + tid);
;             }
.LBB0_141:
	s_mov_b32 s49, s4
	s_mov_b32 s7, s11
	s_mov_b32 s30, s10
	s_mov_b32 s27, s3
	s_mov_b64 s[24:25], -1
	s_cmp_gt_u32 s12, 0x5ff
	s_cbranch_scc1 .LBB0_140
	s_lshr_b32 s3, s12, 3
	s_and_b32 s2, s12, 7
	s_mulk_i32 s2, 0xc0
	s_add_i32 s2, s2, s3
	s_mul_hi_i32 s3, s2, 0x2aaaaaab
	s_lshr_b32 s4, s3, 31
	s_ashr_i32 s3, s3, 4
	s_add_i32 s3, s3, s4
	s_lshl_b32 s4, s3, 3
	s_mulk_i32 s3, 0x60
	s_sub_i32 s2, s2, s3
	s_and_b32 s2, s2, 7
	s_add_i32 s2, s4, s2
	s_cmp_eq_u32 s2, s49
	s_cselect_b64 s[10:11], -1, 0
	s_cmp_eq_u32 s2, s7
	s_cselect_b64 s[18:19], -1, 0
	s_or_b64 s[10:11], s[10:11], s[18:19]
	s_cmp_eq_u32 s2, s30
	s_cselect_b64 s[18:19], -1, 0
	s_or_b64 s[10:11], s[10:11], s[18:19]
	s_cmp_eq_u32 s2, s27
	s_cselect_b64 s[18:19], -1, 0
	s_or_b64 s[10:11], s[10:11], s[18:19]
	s_andn2_b64 vcc, exec, s[10:11]
	s_mov_b32 s4, s49
	s_mov_b32 s11, s7
	s_mov_b32 s10, s30
	s_mov_b32 s3, s27
	s_cbranch_vccz .LBB0_139
	s_cmp_lt_i32 s49, 0
	s_mov_b32 s18, 0
	s_cbranch_scc1 .LBB0_148
	s_cmp_lt_i32 s7, 0
	s_movk_i32 s18, 0x100
	s_cbranch_scc1 .LBB0_149
	s_cmp_lt_i32 s30, 0
	s_movk_i32 s18, 0x200
	s_cbranch_scc1 .LBB0_150
	s_cmp_gt_i32 s27, -1
	s_cbranch_scc0 .LBB0_151
	s_mov_b64 s[24:25], 0
	s_movk_i32 s18, 0xff00
	s_mov_b32 s3, s27
	s_branch .LBB0_152

;     __host__ __device__ bool next(int i, Unit& u) const {
;         const long L = (long)i * G + c; if (L >= nwg) return false;
;         int wgid = (int)L; { const int q = nwg / NXCD, r = nwg % NXCD, xcd = wgid % NXCD, off = wgid / NXCD; wgid = (xcd < r ? xcd * (q + 1) : r * (q + 1) + (xcd - r) * q) + off; }
;         const int nig = WGM * nN, gid = wgid / nig, fm = gid * WGM, gsz = (nM - fm) < WGM ? (nM - fm) : WGM;
;         u.pm = fm + ((wgid % nig) % gsz); u.pn = (wgid % nig) / gsz; return true;
; template <class Epi, class Sched, bool ALIGN_EPI = false, bool SP2 = false>
; __device__ __forceinline__ void gemm_phase(PG8_LAS unsigned char* lds, const Gemm g, const Sched& S, const Epi& E) {
;     ...
;         const bool has_next = S.next(ui + 1, nxt);
;         const char* nA = has_next ? (const char*)g.A + (size_t)nxt.pm * tstepA : cA; const char* nB = has_next ? (const char*)g.Bt + (size_t)nxt.pn * tstepB : cB;
.LBB0_158:
	s_add_i32 s53, s53, 1
	v_readlane_b32 s2, v253, 5
	s_mul_i32 s2, s53, s2
	s_mul_hi_u32 s3, s53, s33
	s_add_i32 s3, s3, s2
	s_mul_i32 s2, s53, s33
	v_readlane_b32 s8, v254, 21
	v_readlane_b32 s9, v254, 22
	s_add_u32 s12, s2, s8
	s_addc_u32 s13, s3, s9
	v_mov_b64_e32 v[0:1], 0x600
	s_mov_b32 s7, s31
	v_cmp_lt_i64_e64 s[30:31], s[12:13], v[0:1]
	v_mov_b64_e32 v[0:1], 0x5ff
	v_cmp_gt_i64_e32 vcc, s[12:13], v[0:1]
	s_mov_b32 s16, s49
	s_cbranch_vccnz .LBB0_160
	s_lshr_b32 s3, s12, 3
	s_and_b32 s2, s12, 7
	s_mulk_i32 s2, 0xc0
	s_add_i32 s2, s2, s3
	s_mul_hi_i32 s3, s2, 0x2aaaaaab
	s_lshr_b32 s8, s3, 31
	s_ashr_i32 s3, s3, 4
	s_add_i32 s3, s3, s8
	s_lshl_b32 s8, s3, 3
	s_mulk_i32 s3, 0x60
	s_sub_i32 s2, s2, s3
	s_ashr_i32 s48, s2, 3
	s_and_b32 s2, s2, 7
	s_add_i32 s54, s8, s2

;     __device__ __forceinline__ float rstd_global(int row) const { return row_rstd(ssq, row); }
;     __device__ __forceinline__ float rstd_global(int row) const { return row_rstd(ssq, row); }
;     __device__ __forceinline__ float rstd_global(int row) const { return row_rstd(ssq, row); }
;     __host__ __device__ bool next(int i, Unit& u) const {
;         const long L = (long)i * G + c; if (L >= nwg) return false;
;         int wgid = (int)L; { const int q = nwg / NXCD, r = nwg % NXCD, xcd = wgid % NXCD, off = wgid / NXCD; wgid = (xcd < r ? xcd * (q + 1) : r * (q + 1) + (xcd - r) * q) + off; }
;         const int nig = WGM * nN, gid = wgid / nig, fm = gid * WGM, gsz = (nM - fm) < WGM ? (nM - fm) : WGM;
;         u.pm = fm + ((wgid % nig) % gsz); u.pn = (wgid % nig) / gsz; return true;
; template <class Epi, class Sched, bool ALIGN_EPI = false, bool SP2 = false>
; __device__ __forceinline__ void gemm_phase(PG8_LAS unsigned char* lds, const Gemm g, const Sched& S, const Epi& E) {
;     ...
;         for (int i = 0; S.next(i, tu); ++i) {
;             const int p = tu.pm;
;             if (p != pmc0 && p != pmc1 && p != pmc2 && p != pmc3) {
;                 int slot = -1;
;                 if (pmc0 < 0) { pmc0 = p; slot = 0; } else if (pmc1 < 0) { pmc1 = p; slot = 1; } else if (pmc2 < 0) { pmc2 = p; slot = 2; } else if (pmc3 < 0) { pmc3 = p; slot = 3; }
;                 if (slot >= 0 && tid < 256) rt[slot * 256 + tid] = E.rstd_global(p * 256 + tid);
;             }
.LBB0_230:
	s_mov_b32 s6, s10
	s_mov_b32 s7, s18
	s_mov_b32 s8, s11
	s_mov_b32 s9, s3
	s_mov_b64 s[24:25], -1
	s_cmp_gt_u32 s16, 0x5ff
	s_cbranch_scc1 .LBB0_229
	s_lshr_b32 s3, s16, 3
	s_and_b32 s2, s16, 7
	s_mulk_i32 s2, 0xc0
	s_add_i32 s2, s2, s3
	s_mul_hi_i32 s3, s2, 0x2aaaaaab
	s_lshr_b32 s10, s3, 31
	s_ashr_i32 s3, s3, 4
	s_add_i32 s3, s3, s10
	s_lshl_b32 s10, s3, 3
	s_mulk_i32 s3, 0x60
	s_sub_i32 s2, s2, s3
	s_and_b32 s2, s2, 7
	s_add_i32 s2, s10, s2
	s_cmp_eq_u32 s2, s6
	s_cselect_b64 s[10:11], -1, 0
	s_cmp_eq_u32 s2, s7
	s_cselect_b64 s[18:19], -1, 0
	s_or_b64 s[10:11], s[10:11], s[18:19]
	s_cmp_eq_u32 s2, s8
	s_cselect_b64 s[18:19], -1, 0
	s_or_b64 s[10:11], s[10:11], s[18:19]
	s_cmp_eq_u32 s2, s9
	s_cselect_b64 s[18:19], -1, 0
	s_or_b64 s[10:11], s[10:11], s[18:19]
	s_andn2_b64 vcc, exec, s[10:11]
	s_mov_b32 s10, s6
	s_mov_b32 s18, s7
	s_mov_b32 s11, s8
	s_mov_b32 s3, s9
	s_cbranch_vccz .LBB0_228
	s_cmp_lt_i32 s6, 0
	s_mov_b32 s19, 0
	s_cbranch_scc1 .LBB0_237
	s_cmp_lt_i32 s7, 0
	s_movk_i32 s19, 0x100
	s_cbranch_scc1 .LBB0_238
	s_cmp_lt_i32 s8, 0
	s_movk_i32 s19, 0x200
	s_cbranch_scc1 .LBB0_239
	s_cmp_gt_i32 s9, -1
	s_cbranch_scc0 .LBB0_240
	s_mov_b64 s[24:25], 0
	s_movk_i32 s19, 0xff00
	s_mov_b32 s3, s9
	s_branch .LBB0_241

;     __host__ __device__ bool next(int i, Unit& u) const {
;         const long L = (long)i * G + c; if (L >= nwg) return false;
;         int wgid = (int)L; { const int q = nwg / NXCD, r = nwg % NXCD, xcd = wgid % NXCD, off = wgid / NXCD; wgid = (xcd < r ? xcd * (q + 1) : r * (q + 1) + (xcd - r) * q) + off; }
;         const int nig = WGM * nN, gid = wgid / nig, fm = gid * WGM, gsz = (nM - fm) < WGM ? (nM - fm) : WGM;
;         u.pm = fm + ((wgid % nig) % gsz); u.pn = (wgid % nig) / gsz; return true;
; template <class Epi, class Sched, bool ALIGN_EPI = false, bool SP2 = false>
; __device__ __forceinline__ void gemm_phase(PG8_LAS unsigned char* lds, const Gemm g, const Sched& S, const Epi& E) {
;     ...
;         const bool has_next = S.next(ui + 1, nxt);
;         const char* nA = has_next ? (const char*)g.A + (size_t)nxt.pm * tstepA : cA; const char* nB = has_next ? (const char*)g.Bt + (size_t)nxt.pn * tstepB : cB;
.LBB0_247:
	s_add_i32 s97, s97, 1
	v_readlane_b32 s2, v253, 5
	s_mul_i32 s2, s97, s2
	s_mul_hi_u32 s3, s97, s33
	s_add_i32 s3, s3, s2
	s_mul_i32 s2, s97, s33
	v_readlane_b32 s12, v254, 21
	v_readlane_b32 s13, v254, 22
	s_add_u32 s28, s2, s12
	s_addc_u32 s29, s3, s13
	v_mov_b64_e32 v[0:1], 0x600
	v_cmp_lt_i64_e64 s[40:41], s[28:29], v[0:1]
	v_mov_b64_e32 v[0:1], 0x5ff
	v_cmp_gt_i64_e32 vcc, s[28:29], v[0:1]
	s_cbranch_vccnz .LBB0_249
	s_lshr_b32 s3, s28, 3
	s_and_b32 s2, s28, 7
	s_mulk_i32 s2, 0xc0
	s_add_i32 s2, s2, s3
	s_mul_hi_i32 s3, s2, 0x2aaaaaab
	s_lshr_b32 s11, s3, 31
	s_ashr_i32 s3, s3, 4
	s_add_i32 s3, s3, s11
	s_lshl_b32 s11, s3, 3
	s_mulk_i32 s3, 0x60
	s_sub_i32 s2, s2, s3
	s_ashr_i32 s46, s2, 3
	s_and_b32 s2, s2, 7
	s_add_i32 s48, s11, s2

;     __device__ __forceinline__ float rstd_global(int row) const { return row_rstd(ssq, row); }
;     __device__ __forceinline__ float rstd_global(int row) const { return row_rstd(ssq, row); }
;     __device__ __forceinline__ float rstd_global(int row) const { return row_rstd(ssq, row); }
;     __host__ __device__ bool next(int i, Unit& u) const {
;         const long L = (long)i * G + c; if (L >= nwg) return false;
;         int wgid = (int)L; { const int q = nwg / NXCD, r = nwg % NXCD, xcd = wgid % NXCD, off = wgid / NXCD; wgid = (xcd < r ? xcd * (q + 1) : r * (q + 1) + (xcd - r) * q) + off; }
;         const int nig = WGM * nN, gid = wgid / nig, fm = gid * WGM, gsz = (nM - fm) < WGM ? (nM - fm) : WGM;
;         u.pm = fm + ((wgid % nig) % gsz); u.pn = (wgid % nig) / gsz; return true;
; template <class Epi, class Sched, bool ALIGN_EPI = false, bool SP2 = false>
; __device__ __forceinline__ void gemm_phase(PG8_LAS unsigned char* lds, const Gemm g, const Sched& S, const Epi& E) {
;     ...
;         for (int i = 0; S.next(i, tu); ++i) {
;             const int p = tu.pm;
;             if (p != pmc0 && p != pmc1 && p != pmc2 && p != pmc3) {
;                 int slot = -1;
;                 if (pmc0 < 0) { pmc0 = p; slot = 0; } else if (pmc1 < 0) { pmc1 = p; slot = 1; } else if (pmc2 < 0) { pmc2 = p; slot = 2; } else if (pmc3 < 0) { pmc3 = p; slot = 3; }
;                 if (slot >= 0 && tid < 256) rt[slot * 256 + tid] = E.rstd_global(p * 256 + tid);
;             }
.LBB0_458:
	s_mov_b32 s4, s9
	s_mov_b32 s6, s11
	s_mov_b32 s7, s10
	s_mov_b32 s8, s3
	s_mov_b64 s[24:25], -1
	s_cmp_gt_u32 s16, 0xaff
	s_cbranch_scc1 .LBB0_457
	s_lshr_b32 s3, s16, 3
	s_and_b32 s2, s16, 7
	s_mulk_i32 s2, 0x160
	s_add_i32 s2, s2, s3
	s_mul_hi_i32 s3, s2, 0x2e8ba2e9
	s_lshr_b32 s9, s3, 31
	s_ashr_i32 s3, s3, 5
	s_add_i32 s3, s3, s9
	s_lshl_b32 s9, s3, 3
	s_mulk_i32 s3, 0xb0
	s_sub_i32 s2, s2, s3
	s_and_b32 s2, s2, 7
	s_add_i32 s2, s9, s2
	s_cmp_eq_u32 s2, s4
	s_cselect_b64 s[10:11], -1, 0
	s_cmp_eq_u32 s2, s6
	s_cselect_b64 s[18:19], -1, 0
	s_or_b64 s[10:11], s[10:11], s[18:19]
	s_cmp_eq_u32 s2, s7
	s_cselect_b64 s[18:19], -1, 0
	s_or_b64 s[10:11], s[10:11], s[18:19]
	s_cmp_eq_u32 s2, s8
	s_cselect_b64 s[18:19], -1, 0
	s_or_b64 s[10:11], s[10:11], s[18:19]
	s_andn2_b64 vcc, exec, s[10:11]
	s_mov_b32 s9, s4
	s_mov_b32 s11, s6
	s_mov_b32 s10, s7
	s_mov_b32 s3, s8
	s_cbranch_vccz .LBB0_456
	s_cmp_lt_i32 s4, 0
	s_mov_b32 s18, 0
	s_cbranch_scc1 .LBB0_465
	s_cmp_lt_i32 s6, 0
	s_movk_i32 s18, 0x100
	s_cbranch_scc1 .LBB0_466
	s_cmp_lt_i32 s7, 0
	s_movk_i32 s18, 0x200
	s_cbranch_scc1 .LBB0_467
	s_cmp_gt_i32 s8, -1
	s_cbranch_scc0 .LBB0_468
	s_mov_b64 s[24:25], 0
	s_movk_i32 s18, 0xff00
	s_mov_b32 s3, s8
	s_branch .LBB0_469

;     __host__ __device__ bool next(int i, Unit& u) const {
;         const long L = (long)i * G + c; if (L >= nwg) return false;
;         int wgid = (int)L; { const int q = nwg / NXCD, r = nwg % NXCD, xcd = wgid % NXCD, off = wgid / NXCD; wgid = (xcd < r ? xcd * (q + 1) : r * (q + 1) + (xcd - r) * q) + off; }
;         const int nig = WGM * nN, gid = wgid / nig, fm = gid * WGM, gsz = (nM - fm) < WGM ? (nM - fm) : WGM;
;         u.pm = fm + ((wgid % nig) % gsz); u.pn = (wgid % nig) / gsz; return true;
; template <class Epi, class Sched, bool ALIGN_EPI = false, bool SP2 = false>
; __device__ __forceinline__ void gemm_phase(PG8_LAS unsigned char* lds, const Gemm g, const Sched& S, const Epi& E) {
;     ...
;         const bool has_next = S.next(ui + 1, nxt);
;         const char* nA = has_next ? (const char*)g.A + (size_t)nxt.pm * tstepA : cA; const char* nB = has_next ? (const char*)g.Bt + (size_t)nxt.pn * tstepB : cB;
.LBB0_475:
	s_add_i32 s54, s54, 1
	v_readlane_b32 s2, v253, 5
	s_mul_i32 s2, s54, s2
	s_mul_hi_u32 s3, s54, s33
	s_add_i32 s3, s3, s2
	s_mul_i32 s2, s54, s33
	v_readlane_b32 s10, v254, 21
	v_readlane_b32 s11, v254, 22
	s_add_u32 s28, s2, s10
	s_addc_u32 s29, s3, s11
	v_mov_b64_e32 v[0:1], 0xb00
	v_cmp_lt_i64_e64 s[40:41], s[28:29], v[0:1]
	v_mov_b64_e32 v[0:1], 0xaff
	v_cmp_gt_i64_e32 vcc, s[28:29], v[0:1]
	s_cbranch_vccnz .LBB0_477
	s_lshr_b32 s3, s28, 3
	s_and_b32 s2, s28, 7
	s_mulk_i32 s2, 0x160
	s_add_i32 s2, s2, s3
	s_mul_hi_i32 s3, s2, 0x2e8ba2e9
	s_lshr_b32 s10, s3, 31
	s_ashr_i32 s3, s3, 5
	s_add_i32 s3, s3, s10
	s_lshl_b32 s10, s3, 3
	s_mulk_i32 s3, 0xb0
	s_sub_i32 s2, s2, s3
	s_ashr_i32 s24, s2, 3
	s_and_b32 s2, s2, 7
	s_add_i32 s26, s10, s2
